# weight-conversion (f32 -> bf16 transposed) stores write-through (sc1) in prep and in the FFN-in tail half-rounds
# baseline (speedup 1.0000x reference)
.LBB0_51:
	s_ashr_i32 s19, s18, 31
	s_lshl_b64 s[10:11], s[18:19], 1
	s_add_u32 s8, s8, s10
	s_addc_u32 s9, s9, s11
	v_mov_b32_e32 v3, v161
	ds_read2_b32 v[8:9], v40 offset0:33 offset1:41
	ds_read2_b32 v[10:11], v40 offset1:8
	ds_read2_b32 v[12:13], v40 offset0:66 offset1:74
	ds_read2_b32 v[14:15], v40 offset0:99 offset1:107
	ds_read2_b32 v[16:17], v40 offset0:132 offset1:140
	ds_read2_b32 v[18:19], v40 offset0:165 offset1:173
	ds_read2_b32 v[20:21], v40 offset0:198 offset1:206
	ds_read2_b32 v[22:23], v40 offset0:231 offset1:239
	v_lshl_add_u64 v[24:25], s[8:9], 0, v[2:3]
	v_add_u32_e32 v3, s14, v39
	s_waitcnt lgkmcnt(6)
	v_cvt_pk_bf16_f32 v4, v10, v8
	v_ashrrev_i32_e32 v8, 31, v3
	v_mul_lo_u32 v8, s6, v8
	v_mul_lo_u32 v10, s7, v3
	v_mad_u64_u32 v[26:27], s[8:9], s6, v3, 0
	v_add3_u32 v27, v27, v8, v10
	v_add_u32_e32 v3, s14, v41
	s_waitcnt lgkmcnt(4)
	v_cvt_pk_bf16_f32 v5, v12, v14
	s_waitcnt lgkmcnt(2)
	v_cvt_pk_bf16_f32 v6, v16, v18
	s_waitcnt lgkmcnt(0)
	v_cvt_pk_bf16_f32 v7, v20, v22
	v_lshl_add_u64 v[26:27], v[26:27], 1, v[24:25]
	v_ashrrev_i32_e32 v8, 31, v3
	global_store_dwordx4 v[26:27], v[4:7], off sc1
	v_mul_lo_u32 v10, s6, v8
	s_add_i32 s24, s24, s34
	v_cvt_pk_bf16_f32 v4, v11, v9
	v_mul_lo_u32 v11, s7, v3
	v_mad_u64_u32 v[8:9], s[8:9], s6, v3, 0
	v_cvt_pk_bf16_f32 v5, v13, v15
	v_cvt_pk_bf16_f32 v6, v17, v19
	v_cvt_pk_bf16_f32 v7, v21, v23
	v_add3_u32 v9, v9, v10, v11
	ds_read2_b32 v[10:11], v40 offset0:49 offset1:57
	ds_read2_b32 v[12:13], v40 offset0:16 offset1:24
	ds_read2_b32 v[14:15], v40 offset0:82 offset1:90
	ds_read2_b32 v[16:17], v40 offset0:115 offset1:123
	ds_read2_b32 v[18:19], v40 offset0:148 offset1:156
	ds_read2_b32 v[20:21], v40 offset0:181 offset1:189
	ds_read2_b32 v[22:23], v40 offset0:214 offset1:222
	ds_read2_b32 v[26:27], v40 offset0:247 offset1:255
	v_lshl_add_u64 v[8:9], v[8:9], 1, v[24:25]
	v_add_u32_e32 v3, s14, v42
	global_store_dwordx4 v[8:9], v[4:7], off sc1
	v_ashrrev_i32_e32 v8, 31, v3
	s_cmpk_gt_i32 s24, 0x2e3f
	s_waitcnt lgkmcnt(6)
	v_cvt_pk_bf16_f32 v4, v12, v10
	v_mul_lo_u32 v10, s6, v8
	v_mul_lo_u32 v12, s7, v3
	v_mad_u64_u32 v[8:9], s[8:9], s6, v3, 0
	v_add3_u32 v9, v9, v10, v12
	s_waitcnt lgkmcnt(4)
	v_cvt_pk_bf16_f32 v5, v14, v16
	s_waitcnt lgkmcnt(2)
	v_cvt_pk_bf16_f32 v6, v18, v20
	s_waitcnt lgkmcnt(0)
	v_cvt_pk_bf16_f32 v7, v22, v26
	v_lshl_add_u64 v[8:9], v[8:9], 1, v[24:25]
	v_add_u32_e32 v3, s14, v43
	global_store_dwordx4 v[8:9], v[4:7], off sc1
	v_ashrrev_i32_e32 v8, 31, v3
	v_mul_lo_u32 v10, s6, v8
	v_cvt_pk_bf16_f32 v4, v13, v11
	v_mul_lo_u32 v11, s7, v3
	v_mad_u64_u32 v[8:9], s[6:7], s6, v3, 0
	v_add3_u32 v9, v9, v10, v11
	v_cvt_pk_bf16_f32 v5, v15, v17
	v_cvt_pk_bf16_f32 v6, v19, v21
	v_cvt_pk_bf16_f32 v7, v23, v27
	v_lshl_add_u64 v[8:9], v[8:9], 1, v[24:25]
	global_store_dwordx4 v[8:9], v[4:7], off sc1
	s_waitcnt lgkmcnt(0)
	s_cbranch_scc1 .LBB0_95
